# attention loop step heads: K/Q fragment reads issued first after the barrier, LDS-DMA issues moved behind MFMAs 1-3
# speedup vs baseline: 1.0233x; 1.0037x over previous
; #define A128_WAITBAR() asm volatile("s_waitcnt vmcnt(0) lgkmcnt(0)\n\ts_barrier":::"memory")
; #define SB() __builtin_amdgcn_sched_barrier(0)
; #define MF32(a,b,c) __builtin_amdgcn_mfma_f32_32x32x16_bf16(a,b,c,0,0,0)
; #define EXP1(x) x=__builtin_amdgcn_exp2f((x)-mh_)
;   #define QF(d0) LDSQ(qp+(d0)*1024)
; template<int THRL,bool FIRST> __device__ __forceinline__ void step_main(f32x16&p0,f32x16&p1,f32x16&n0,f32x16&n1,St&S,lds_cptr kpn,lds_cptr qp,lds_cptr vp,float*wsf,int r32,int hi,float&rm){
;     ...
;   bf16x8 ka=KF(0),kb=KF(1),kc=KF(2),kd=KF(3),qa=QF(0),qb=QF(1);
;   decide<THRL,FIRST>(rm,S,wsf,r32,hi);
;   u32x4 pw0,pw1,pw2,pw3; const float mh_=S.mhat; const f32x16 z=f32x16{};
;   SB();
;   n0=MF32(ka,qa,z); ka=KF(4); EXP1(p0[0]);EXP1(p0[1]);EXP1(p0[2]); SB();
;   n1=MF32(kb,qa,z); kb=KF(5); qa=QF(2); EXP1(p0[3]);EXP1(p0[4]);EXP1(p0[5]); SB();
;   n0=MF32(kc,qb,n0);   kc=KF(6); EXP1(p0[6]);EXP1(p0[7]);EXP1(p0[8]); SB();
;   n1=MF32(kd,qb,n1);   kd=KF(7); qb=QF(3); EXP1(p0[9]);EXP1(p0[10]);EXP1(p0[11]); SB();
;   bf16x8 vfa=vfrag(vp,0);
;   n0=MF32(ka,qa,n0);   EXP1(p0[12]);EXP1(p0[13]);EXP1(p0[14]); pw0=packw(p0,0); SB();
;   bf16x8 vfb=vfrag(vp,1);
;   n1=MF32(kb,qa,n1);   EXP1(p0[15]);EXP1(p1[0]);EXP1(p1[1]); SB();
;   bf16x8 vfc=vfrag(vp,2);
;   n0=MF32(kc,qb,n0);   EXP1(p1[2]);EXP1(p1[3]);EXP1(p1[4]); pw1=packw(p0,8); SB();
;   bf16x8 vfd=vfrag(vp,3);
;   n1=MF32(kd,qb,n1);   EXP1(p1[5]);EXP1(p1[6]);EXP1(p1[7]); SB();
;     ...
;   float sa=p0[0]+p0[1];
;     ...
;   PVG(0,pw0,vfa,4, p0[2],p0[3],p0[4],p0[5],   do{EXP1(p1[8]);EXP1(p1[9]);}while(0));
;   PVG(1,pw0,vfb,5, p0[6],p0[7],p0[8],p0[9], do{EXP1(p1[10]);EXP1(p1[11]);}while(0));
;   PVG(2,pw0,vfc,6, p0[10],p0[11],p0[12],p0[13], do{EXP1(p1[12]);EXP1(p1[13]);}while(0));
;   PVG(3,pw0,vfd,7, p0[14],p0[15],p1[0],p1[1],   do{EXP1(p1[14]);EXP1(p1[15]);}while(0));
;   PVG(4,pw1,vfa,8, p1[2],p1[3],p1[4],p1[5],   pw2=packw(p1,0));
;   PVG(5,pw1,vfb,9, p1[6],p1[7],p1[8],p1[9], pw3=packw(p1,8));
;   PVG(6,pw1,vfc,10, p1[10],p1[11],p1[12],p1[13], do{}while(0));
;   PVG(7,pw1,vfd,11, p1[14],p1[15],0.f,0.f, do{}while(0));
; template<int THRL> __device__ __forceinline__ void unit(int qb,const bf16*Q,const bf16*K,const bf16*V,bf16*O,char*shm){
;     ...
;       DMA_K(t+2,ks2); DMA_V(t+1,VBUF);
;       step_main<THRL,false>(pA0,pA1,pB0,pB1,S,kp0+ks1,qp,vp0,wsf,r32,hi,rm); A128_WAITBAR(); ROT();
;       DMA_K(t+3,ks2); DMA_V(t+2,0);
.LBB0_277:
	s_add_i32 s90, s90, 2
	s_waitcnt lgkmcnt(1)
	v_mfma_f32_32x32x16_bf16 v[98:113], v[90:93], v[86:89], v[146:161]
	s_add_i32 s4, s91, s84
	s_mov_b32 s5, m0
	s_mov_b32 m0, s4
	s_nop 0
	global_load_lds_dwordx4 v252, s[58:59]
	s_mov_b32 m0, s5
	v_exp_f32_e32 v130, v130
	v_exp_f32_e32 v131, v131
	ds_read_b128 v[180:183], v178 offset:4096
	v_exp_f32_e32 v132, v132
	v_exp_f32_e32 v133, v133
	v_exp_f32_e32 v134, v134
	v_exp_f32_e32 v135, v135
	v_mfma_f32_32x32x16_bf16 v[82:97], v[82:85], v[86:89], v[146:161]
	ds_read_b128 v[184:187], v178 offset:4608
	ds_read_b128 v[188:191], v248 offset:2048
	s_add_u32 s60, s50, 0xc0000
	s_addc_u32 s61, s51, 0
	s_mov_b32 s4, m0
	s_mov_b32 m0, s80
	s_nop 0
	global_load_lds_dwordx4 v250, s[60:61]
	s_mov_b32 m0, s4
	s_waitcnt lgkmcnt(3)
	v_mfma_f32_32x32x16_bf16 v[98:113], v[12:15], v[8:11], v[98:113]
	ds_read_b128 v[192:195], v178 offset:6144
	s_add_u32 s60, s50, 0xc0080
	s_addc_u32 s61, s51, 0
	s_mov_b32 s4, m0
	s_mov_b32 m0, s83
	s_nop 0
	global_load_lds_dwordx4 v250, s[60:61]
	s_mov_b32 m0, s4
	v_exp_f32_e32 v136, v136
	v_exp_f32_e32 v137, v137
	v_exp_f32_e32 v138, v138
	v_mfma_f32_32x32x16_bf16 v[82:97], v[4:7], v[8:11], v[82:97]
	ds_read_b128 v[12:15], v178 offset:6656
	ds_read_b128 v[196:199], v248 offset:3072
	v_exp_f32_e32 v139, v139
	v_exp_f32_e32 v140, v140
	v_exp_f32_e32 v141, v141
	s_waitcnt lgkmcnt(3)
	v_mfma_f32_32x32x16_bf16 v[98:113], v[180:183], v[188:191], v[98:113]
	v_exp_f32_e32 v142, v142
	ds_read_b64_tr_b16 v[4:5], v246 offset:40960
	ds_read_b64_tr_b16 v[6:7], v246 offset:41472
	v_exp_f32_e32 v143, v143
	v_exp_f32_e32 v144, v144
	v_cvt_pk_bf16_f32 v8, v130, v131
	v_cvt_pk_bf16_f32 v9, v132, v133
	v_cvt_pk_bf16_f32 v10, v134, v135
	v_cvt_pk_bf16_f32 v11, v136, v137
	v_mfma_f32_32x32x16_bf16 v[82:97], v[184:187], v[188:191], v[82:97]
	ds_read_b64_tr_b16 v[178:179], v246 offset:45056
	ds_read_b64_tr_b16 v[180:181], v246 offset:45568
	v_exp_f32_e32 v145, v145
	v_exp_f32_e32 v114, v114
	v_exp_f32_e32 v115, v115
	s_waitcnt lgkmcnt(4)
	v_mfma_f32_32x32x16_bf16 v[98:113], v[192:195], v[196:199], v[98:113]
	ds_read_b64_tr_b16 v[182:183], v246 offset:49152
	ds_read_b64_tr_b16 v[184:185], v246 offset:49664
	v_exp_f32_e32 v116, v116
	v_exp_f32_e32 v117, v117
	v_exp_f32_e32 v118, v118
	v_cvt_pk_bf16_f32 v186, v138, v139
	v_cvt_pk_bf16_f32 v187, v140, v141
	v_cvt_pk_bf16_f32 v188, v142, v143
	v_cvt_pk_bf16_f32 v189, v144, v145
	v_mfma_f32_32x32x16_bf16 v[82:97], v[12:15], v[196:199], v[82:97]
	ds_read_b64_tr_b16 v[190:191], v246 offset:53248
	ds_read_b64_tr_b16 v[192:193], v246 offset:53760
	v_exp_f32_e32 v119, v119
	v_exp_f32_e32 v120, v120
	v_exp_f32_e32 v121, v121
	s_waitcnt lgkmcnt(6)
	v_mfma_f32_32x32x16_bf16 v[18:33], v[8:11], v[4:7], v[18:33]
	ds_read_b64_tr_b16 v[12:13], v246 offset:41984
	ds_read_b64_tr_b16 v[14:15], v246 offset:42496
	v_add_f32_e32 v194, v130, v131
	v_exp_f32_e32 v122, v122
	v_exp_f32_e32 v123, v123
	v_add_f32_e32 v194, v132, v194
	v_add_f32_e32 v4, v133, v194
	v_add_f32_e32 v4, v134, v4
	v_add_f32_e32 v194, v135, v4
	s_waitcnt lgkmcnt(6)
	v_mfma_f32_32x32x16_bf16 v[34:49], v[8:11], v[178:181], v[34:49]
	ds_read_b64_tr_b16 v[4:5], v246 offset:46080
	ds_read_b64_tr_b16 v[6:7], v246 offset:46592
	v_exp_f32_e32 v124, v124
	v_exp_f32_e32 v125, v125
	v_add_f32_e32 v194, v136, v194
	v_add_f32_e32 v178, v137, v194
	v_add_f32_e32 v178, v138, v178
	v_add_f32_e32 v194, v139, v178
	s_waitcnt lgkmcnt(6)
	v_mfma_f32_32x32x16_bf16 v[50:65], v[8:11], v[182:185], v[50:65]
	ds_read_b64_tr_b16 v[178:179], v246 offset:50176
	ds_read_b64_tr_b16 v[180:181], v246 offset:50688
	v_exp_f32_e32 v126, v126
	v_exp_f32_e32 v127, v127
	v_add_f32_e32 v194, v140, v194
	v_add_f32_e32 v182, v141, v194
	v_add_f32_e32 v182, v142, v182
	v_add_f32_e32 v194, v143, v182
	s_waitcnt lgkmcnt(6)
	v_mfma_f32_32x32x16_bf16 v[66:81], v[8:11], v[190:193], v[66:81]
	ds_read_b64_tr_b16 v[182:183], v246 offset:54272
	ds_read_b64_tr_b16 v[184:185], v246 offset:54784
	v_exp_f32_e32 v128, v128
	v_exp_f32_e32 v129, v129
	v_add_f32_e32 v194, v144, v194
	v_add_f32_e32 v8, v145, v194
	v_add_f32_e32 v8, v114, v8
	v_add_f32_e32 v190, v115, v8
	s_waitcnt lgkmcnt(6)
	v_mfma_f32_32x32x16_bf16 v[18:33], v[186:189], v[12:15], v[18:33]
	ds_read_b64_tr_b16 v[8:9], v246 offset:43008
	ds_read_b64_tr_b16 v[10:11], v246 offset:43520
	v_add_f32_e32 v190, v116, v190
	v_add_f32_e32 v190, v117, v190
	v_add_f32_e32 v190, v118, v190
	v_add_f32_e32 v194, v119, v190
	v_cvt_pk_bf16_f32 v12, v114, v115
	v_cvt_pk_bf16_f32 v13, v116, v117
	v_cvt_pk_bf16_f32 v14, v118, v119
	v_cvt_pk_bf16_f32 v15, v120, v121
	s_waitcnt lgkmcnt(6)
	v_mfma_f32_32x32x16_bf16 v[34:49], v[186:189], v[4:7], v[34:49]
	ds_read_b64_tr_b16 v[190:191], v246 offset:47104
	ds_read_b64_tr_b16 v[192:193], v246 offset:47616
	v_add_f32_e32 v194, v120, v194
	v_add_f32_e32 v194, v121, v194
	v_add_f32_e32 v194, v122, v194
	v_add_f32_e32 v198, v123, v194
	v_cvt_pk_bf16_f32 v4, v122, v123
	v_cvt_pk_bf16_f32 v5, v124, v125
	v_cvt_pk_bf16_f32 v6, v126, v127
	v_cvt_pk_bf16_f32 v7, v128, v129
	s_waitcnt lgkmcnt(6)
	v_mfma_f32_32x32x16_bf16 v[50:65], v[186:189], v[178:181], v[50:65]
	ds_read_b64_tr_b16 v[194:195], v246 offset:51200
	ds_read_b64_tr_b16 v[196:197], v246 offset:51712
	v_add_f32_e32 v198, v124, v198
	v_add_f32_e32 v198, v125, v198
	v_add_f32_e32 v198, v126, v198
	v_add_f32_e32 v198, v127, v198
	s_waitcnt lgkmcnt(6)
	v_mfma_f32_32x32x16_bf16 v[66:81], v[186:189], v[182:185], v[66:81]
	ds_read_b64_tr_b16 v[178:179], v246 offset:55296
	ds_read_b64_tr_b16 v[180:181], v246 offset:55808
	v_add_f32_e32 v198, v128, v198
	v_add_f32_e32 v198, v129, v198
	v_add_f32_e32 v198, 0, v198
	s_waitcnt lgkmcnt(6)
; __device__ __forceinline__ int crow(int r,int hi){return (r&3)+8*(r>>2)+4*hi;}
; __device__ __forceinline__ float max3f(float a,float b,float c){float r;asm("v_max3_f32 %0, %1, %2, %3":"=v"(r):"v"(a),"v"(b),"v"(c));return r;}
; __device__ __forceinline__ float max2f(float a,float b){float r;asm("v_max_f32_e32 %0, %1, %2":"=v"(r):"v"(a),"v"(b));return r;}
;   #define PVG(i,PW,VF,NEXTI,X0,X1,Y0,Y1,EXTRA) do{ S.o[(i)&3]=MF32(__builtin_bit_cast(bf16x8,PW),VF,S.o[(i)&3]); if((NEXTI)<16){ VF=vfrag(vp,(NEXTI)<16?(NEXTI):0); } sa+=X0; sa+=X1; sa+=Y0; sa+=Y1; EXTRA; SB(); }while(0)
; template<int THRL,bool FIRST> __device__ __forceinline__ void decide(float rm,St&S,float*wsf,int r32,int hi){
;   if(FIRST){ S.mhat=rm; }
;   else if(__any(rm-S.mhat>(float)THRL)){
;     const float dl=__builtin_fmaxf(rm-S.mhat,0.f); S.mhat+=dl;
;     const float f=__builtin_amdgcn_exp2f(-dl); S.l_reg*=f; if(hi==0)wsf[r32]=f;
;     asm volatile("s_waitcnt lgkmcnt(0)":::"memory");
;     #pragma unroll
;     for(int r=0;r<16;++r){ const float fr=wsf[crow(r,hi)];
;       #pragma unroll
;       for(int d=0;d<4;++d)S.o[d][r]*=fr; }
; template<int THRL,bool FIRST> __device__ __forceinline__ void step_main(f32x16&p0,f32x16&p1,f32x16&n0,f32x16&n1,St&S,lds_cptr kpn,lds_cptr qp,lds_cptr vp,float*wsf,int r32,int hi,float&rm){
;     ...
;   PVG(8,pw2,vfa,12,0.f,0.f,0.f,0.f, do{ma=max3f(n0[0],n0[1],n1[0]);mb=max3f(n0[2],n0[3],n1[1]);PINAB();}while(0));
;   PVG(9,pw2,vfb,13,0.f,0.f,0.f,0.f, do{ma=max3f(ma,n1[2],n1[3]);mb=max3f(mb,n0[4],n0[5]);PINAB();}while(0));
;   PVG(10,pw2,vfc,14,0.f,0.f,0.f,0.f, do{ma=max3f(ma,n0[6],n0[7]);mb=max3f(mb,n1[4],n1[5]);PINAB();}while(0));
;   PVG(11,pw2,vfd,15,0.f,0.f,0.f,0.f, do{ma=max3f(ma,n1[6],n1[7]);mb=max3f(mb,n0[8],n0[9]);PINAB();}while(0));
;   PVG(12,pw3,vfa,16,0.f,0.f,0.f,0.f, do{ma=max3f(ma,n0[10],n0[11]);mb=max3f(mb,n1[8],n1[9]);PINAB();}while(0));
;   PVG(13,pw3,vfb,16,0.f,0.f,0.f,0.f, do{ma=max3f(ma,n1[10],n1[11]);mb=max3f(mb,n0[12],n0[13]);PINAB();}while(0));
;   PVG(14,pw3,vfc,16,0.f,0.f,0.f,0.f, do{ma=max3f(ma,n0[14],n0[15]);mb=max3f(mb,n1[12],n1[13]);PINAB();}while(0));
;   PVG(15,pw3,vfd,16,0.f,0.f,0.f,0.f, do{ma=max3f(ma,n1[14],n1[15]);ma=max2f(ma,mb);PINAB();}while(0));
;     ...
;   { auto rr=__builtin_amdgcn_permlane32_swap(__float_as_uint(ma),__float_as_uint(ma),false,false); rm=max2f(__uint_as_float(rr[0]),__uint_as_float(rr[1])); }
;     ...
;   S.l_reg+=sa;
; }
	v_mfma_f32_32x32x16_bf16 v[18:33], v[12:15], v[8:11], v[18:33]
	ds_read_b64_tr_b16 v[182:183], v246 offset:44032
	ds_read_b64_tr_b16 v[184:185], v246 offset:44544
	v_max3_f32 v186, v98, v99, v82
	v_max3_f32 v187, v100, v101, v83
	s_nop 0
	s_waitcnt lgkmcnt(6)
	v_mfma_f32_32x32x16_bf16 v[34:49], v[12:15], v[190:193], v[34:49]
	ds_read_b64_tr_b16 v[8:9], v246 offset:48128
	ds_read_b64_tr_b16 v[10:11], v246 offset:48640
	v_max3_f32 v199, v186, v84, v85
	v_max3_f32 v200, v187, v102, v103
	s_nop 0
	s_waitcnt lgkmcnt(6)
	v_mfma_f32_32x32x16_bf16 v[50:65], v[12:15], v[194:197], v[50:65]
	ds_read_b64_tr_b16 v[186:187], v246 offset:52224
	ds_read_b64_tr_b16 v[188:189], v246 offset:52736
	v_max3_f32 v199, v199, v104, v105
	v_max3_f32 v200, v200, v86, v87
	s_nop 0
	s_waitcnt lgkmcnt(6)
	v_mfma_f32_32x32x16_bf16 v[66:81], v[12:15], v[178:181], v[66:81]
	ds_read_b64_tr_b16 v[190:191], v246 offset:56320
	ds_read_b64_tr_b16 v[192:193], v246 offset:56832
	v_max3_f32 v194, v199, v88, v89
	v_max3_f32 v195, v200, v106, v107
	s_nop 0
	s_waitcnt lgkmcnt(6)
	v_mfma_f32_32x32x16_bf16 v[18:33], v[4:7], v[182:185], v[18:33]
	v_max3_f32 v12, v194, v108, v109
	v_max3_f32 v13, v195, v90, v91
	s_nop 0
	s_waitcnt lgkmcnt(4)
	v_mfma_f32_32x32x16_bf16 v[34:49], v[4:7], v[8:11], v[34:49]
	v_max3_f32 v12, v12, v92, v93
	v_max3_f32 v13, v13, v110, v111
	s_nop 0
	s_waitcnt lgkmcnt(2)
	v_mfma_f32_32x32x16_bf16 v[50:65], v[4:7], v[186:189], v[50:65]
	v_max3_f32 v8, v12, v112, v113
	v_max3_f32 v9, v13, v94, v95
	s_nop 0
	s_waitcnt lgkmcnt(0)
	v_mfma_f32_32x32x16_bf16 v[66:81], v[4:7], v[190:193], v[66:81]
	v_max3_f32 v8, v8, v96, v97
	s_nop 0
	v_max_f32_e32 v8, v8, v9
	s_nop 0
	s_add_i32 s4, s91, 0x2000
	s_cmpk_lg_i32 s91, 0x4000
	s_cselect_b32 s88, s4, 0
	s_add_u32 s58, s58, 0x180000
	s_addc_u32 s59, s59, 0
	s_add_u32 s50, s50, 0x180000
	s_waitcnt vmcnt(0) lgkmcnt(0)
	s_barrier
	s_addc_u32 s51, s51, 0
	v_mov_b32_e32 v4, v8
	v_add_f32_e32 v251, v17, v198
	s_cmp_lt_u32 s90, s89
	v_permlane32_swap_b32_e32 v8, v4
	v_max_f32_e32 v178, v8, v4
	s_cbranch_scc0 .LBB0_285
.LBB0_278:
	v_add_u32_e32 v17, s91, v249
	ds_read_b128 v[122:125], v17
	ds_read_b128 v[114:117], v17 offset:512
	ds_read_b128 v[12:15], v17 offset:2048
	ds_read_b128 v[4:7], v17 offset:2560
	ds_read_b128 v[118:121], v248
	ds_read_b128 v[8:11], v248 offset:1024
	v_mov_b32_e32 v126, v178
	v_cmp_lt_f32_e32 vcc, s69, v126
	s_cbranch_vccz .LBB0_282
	v_max_f32_e32 v126, v126, v126
	v_max_f32_e32 v126, 0, v126
	v_exp_f32_e64 v127, -v126
	s_and_saveexec_b64 s[60:61], s[6:7]
	ds_write_b32 v16, v127
	s_or_b64 exec, exec, s[60:61]
	s_waitcnt lgkmcnt(0)
	v_add_u32_e32 v140, s78, v2
	ds_read_b128 v[128:131], v140 offset:64
	ds_read_b128 v[132:135], v140 offset:96
	ds_read_b128 v[136:139], v140
	ds_read_b128 v[140:143], v140 offset:32
	v_add_f32_e32 v247, v247, v126
	v_sub_f32_e32 v146, v146, v126
	v_sub_f32_e32 v147, v147, v126
	v_sub_f32_e32 v148, v148, v126
	v_sub_f32_e32 v149, v149, v126
	v_sub_f32_e32 v150, v150, v126
	v_sub_f32_e32 v151, v151, v126
	v_sub_f32_e32 v152, v152, v126
	v_sub_f32_e32 v153, v153, v126
	v_sub_f32_e32 v154, v154, v126
	v_sub_f32_e32 v155, v155, v126
	v_sub_f32_e32 v156, v156, v126
	v_sub_f32_e32 v157, v157, v126
	v_sub_f32_e32 v158, v158, v126
	v_sub_f32_e32 v159, v159, v126
	v_sub_f32_e32 v160, v160, v126
	v_sub_f32_e32 v161, v161, v126
	v_sub_f32_e32 v82, v82, v126
	v_sub_f32_e32 v83, v83, v126
	v_sub_f32_e32 v84, v84, v126
	v_sub_f32_e32 v85, v85, v126
	v_sub_f32_e32 v86, v86, v126
	v_sub_f32_e32 v87, v87, v126
	v_sub_f32_e32 v88, v88, v126
	v_sub_f32_e32 v89, v89, v126
	v_sub_f32_e32 v90, v90, v126
	v_sub_f32_e32 v91, v91, v126
	v_sub_f32_e32 v92, v92, v126
	v_sub_f32_e32 v93, v93, v126
	v_sub_f32_e32 v94, v94, v126
	v_sub_f32_e32 v95, v95, v126
	v_sub_f32_e32 v96, v96, v126
	v_sub_f32_e32 v97, v97, v126
	v_sub_f32_e32 v98, v98, v126
	v_sub_f32_e32 v99, v99, v126
	v_sub_f32_e32 v100, v100, v126
	v_sub_f32_e32 v101, v101, v126
	v_sub_f32_e32 v102, v102, v126
	v_sub_f32_e32 v103, v103, v126
	v_sub_f32_e32 v104, v104, v126
	v_sub_f32_e32 v105, v105, v126
	v_sub_f32_e32 v106, v106, v126
	v_sub_f32_e32 v107, v107, v126
	v_sub_f32_e32 v108, v108, v126
	v_sub_f32_e32 v109, v109, v126
	v_sub_f32_e32 v110, v110, v126
	v_sub_f32_e32 v111, v111, v126
	v_sub_f32_e32 v112, v112, v126
	v_sub_f32_e32 v113, v113, v126
	v_mul_f32_e32 v251, v251, v127
	s_waitcnt lgkmcnt(2)
	v_pk_mul_f32 v[30:31], v[30:31], v[132:133]
	v_pk_mul_f32 v[26:27], v[26:27], v[128:129]
	s_waitcnt lgkmcnt(0)
	v_pk_mul_f32 v[22:23], v[22:23], v[140:141]
	v_pk_mul_f32 v[32:33], v[32:33], v[134:135]
	v_pk_mul_f32 v[28:29], v[28:29], v[130:131]
	v_pk_mul_f32 v[24:25], v[24:25], v[142:143]
	v_pk_mul_f32 v[20:21], v[20:21], v[138:139]
	v_pk_mul_f32 v[18:19], v[18:19], v[136:137]
	v_pk_mul_f32 v[46:47], v[46:47], v[132:133]
	v_pk_mul_f32 v[42:43], v[42:43], v[128:129]
	v_pk_mul_f32 v[38:39], v[38:39], v[140:141]
	v_pk_mul_f32 v[48:49], v[48:49], v[134:135]
	v_pk_mul_f32 v[44:45], v[44:45], v[130:131]
	v_pk_mul_f32 v[40:41], v[40:41], v[142:143]
	v_pk_mul_f32 v[36:37], v[36:37], v[138:139]
	v_pk_mul_f32 v[34:35], v[34:35], v[136:137]
	v_pk_mul_f32 v[62:63], v[62:63], v[132:133]
	v_pk_mul_f32 v[58:59], v[58:59], v[128:129]
	v_pk_mul_f32 v[54:55], v[54:55], v[140:141]
	v_pk_mul_f32 v[64:65], v[64:65], v[134:135]
	v_pk_mul_f32 v[60:61], v[60:61], v[130:131]
	v_pk_mul_f32 v[56:57], v[56:57], v[142:143]
	v_pk_mul_f32 v[52:53], v[52:53], v[138:139]
	v_pk_mul_f32 v[50:51], v[50:51], v[136:137]
	v_pk_mul_f32 v[78:79], v[78:79], v[132:133]
	v_pk_mul_f32 v[74:75], v[74:75], v[128:129]
	v_pk_mul_f32 v[70:71], v[70:71], v[140:141]
	v_pk_mul_f32 v[80:81], v[80:81], v[134:135]
	v_pk_mul_f32 v[76:77], v[76:77], v[130:131]
	v_pk_mul_f32 v[72:73], v[72:73], v[142:143]
	v_pk_mul_f32 v[68:69], v[68:69], v[138:139]
	v_pk_mul_f32 v[66:67], v[66:67], v[136:137]
; #define A128_WAITBAR() asm volatile("s_waitcnt vmcnt(0) lgkmcnt(0)\n\ts_barrier":::"memory")
; #define SB() __builtin_amdgcn_sched_barrier(0)
; #define MF32(a,b,c) __builtin_amdgcn_mfma_f32_32x32x16_bf16(a,b,c,0,0,0)
; #define EXP1(x) x=__builtin_amdgcn_exp2f((x)-mh_)
; __device__ __forceinline__ bf16x8 vfrag(lds_cptr vp,int i){ const s16x4 lo=vtr(vp+(i&3)*4096+(i>>2)*1024), hh=vtr(vp+(i&3)*4096+(i>>2)*1024+512); return (bf16x8){lo[0],lo[1],lo[2],lo[3],hh[0],hh[1],hh[2],hh[3]}; }
;   #define KF(i) LDSQ(kpn+((i)>>1)*2048+((i)&1)*512)
;   #define QF(d0) LDSQ(qp+(d0)*1024)
; template<int THRL,bool FIRST> __device__ __forceinline__ void step_main(f32x16&p0,f32x16&p1,f32x16&n0,f32x16&n1,St&S,lds_cptr kpn,lds_cptr qp,lds_cptr vp,float*wsf,int r32,int hi,float&rm){
;     ...
;   bf16x8 ka=KF(0),kb=KF(1),kc=KF(2),kd=KF(3),qa=QF(0),qb=QF(1);
;   decide<THRL,FIRST>(rm,S,wsf,r32,hi);
;   u32x4 pw0,pw1,pw2,pw3; const float mh_=S.mhat; const f32x16 z=f32x16{};
;   SB();
;   n0=MF32(ka,qa,z); ka=KF(4); EXP1(p0[0]);EXP1(p0[1]);EXP1(p0[2]); SB();
;   n1=MF32(kb,qa,z); kb=KF(5); qa=QF(2); EXP1(p0[3]);EXP1(p0[4]);EXP1(p0[5]); SB();
;   n0=MF32(kc,qb,n0);   kc=KF(6); EXP1(p0[6]);EXP1(p0[7]);EXP1(p0[8]); SB();
;   n1=MF32(kd,qb,n1);   kd=KF(7); qb=QF(3); EXP1(p0[9]);EXP1(p0[10]);EXP1(p0[11]); SB();
;   bf16x8 vfa=vfrag(vp,0);
;   n0=MF32(ka,qa,n0);   EXP1(p0[12]);EXP1(p0[13]);EXP1(p0[14]); pw0=packw(p0,0); SB();
;   bf16x8 vfb=vfrag(vp,1);
;   n1=MF32(kb,qa,n1);   EXP1(p0[15]);EXP1(p1[0]);EXP1(p1[1]); SB();
;   bf16x8 vfc=vfrag(vp,2);
;   n0=MF32(kc,qb,n0);   EXP1(p1[2]);EXP1(p1[3]);EXP1(p1[4]); pw1=packw(p0,8); SB();
;   bf16x8 vfd=vfrag(vp,3);
;   n1=MF32(kd,qb,n1);   EXP1(p1[5]);EXP1(p1[6]);EXP1(p1[7]); SB();
;     ...
;   float sa=p0[0]+p0[1];
;     ...
;   PVG(0,pw0,vfa,4, p0[2],p0[3],p0[4],p0[5],   do{EXP1(p1[8]);EXP1(p1[9]);}while(0));
;   PVG(1,pw0,vfb,5, p0[6],p0[7],p0[8],p0[9], do{EXP1(p1[10]);EXP1(p1[11]);}while(0));
;   PVG(2,pw0,vfc,6, p0[10],p0[11],p0[12],p0[13], do{EXP1(p1[12]);EXP1(p1[13]);}while(0));
;   PVG(3,pw0,vfd,7, p0[14],p0[15],p1[0],p1[1],   do{EXP1(p1[14]);EXP1(p1[15]);}while(0));
; template<int THRL> __device__ __forceinline__ void unit(int qb,const bf16*Q,const bf16*K,const bf16*V,bf16*O,char*shm){
;     ...
;       DMA_K(t+2,ks2); DMA_V(t+1,VBUF);
;       step_main<THRL,false>(pA0,pA1,pB0,pB1,S,kp0+ks1,qp,vp0,wsf,r32,hi,rm); A128_WAITBAR(); ROT();
.LBB0_282:
	s_waitcnt lgkmcnt(1)
	v_mfma_f32_32x32x16_bf16 v[130:145], v[122:125], v[118:121], v[146:161]
	ds_read_b128 v[178:181], v17 offset:4096
	s_add_i32 s4, s88, s84
	s_add_u32 s60, s58, 0xfff40000
	s_addc_u32 s61, s59, -1
	s_mov_b32 s5, m0
	s_mov_b32 m0, s4
	s_nop 0
	global_load_lds_dwordx4 v252, s[60:61]
	s_mov_b32 m0, s5
	v_exp_f32_e32 v190, v98
	v_exp_f32_e32 v191, v99
	v_exp_f32_e32 v192, v100
	v_mfma_f32_32x32x16_bf16 v[114:129], v[114:117], v[118:121], v[146:161]
	ds_read_b128 v[182:185], v17 offset:4608
	ds_read_b128 v[186:189], v248 offset:2048
	s_mov_b32 s4, m0
	s_mov_b32 m0, s79
	s_nop 0
	global_load_lds_dwordx4 v250, s[50:51]
	s_mov_b32 m0, s4
	v_exp_f32_e32 v193, v101
	v_exp_f32_e32 v194, v102
	v_exp_f32_e32 v195, v103
	s_waitcnt lgkmcnt(3)
	v_mfma_f32_32x32x16_bf16 v[130:145], v[12:15], v[8:11], v[130:145]
	ds_read_b128 v[98:101], v17 offset:6144
	s_add_u32 s60, s50, 0x80
	s_addc_u32 s61, s51, 0
	s_mov_b32 s4, m0
	s_mov_b32 m0, s41
	s_nop 0
	global_load_lds_dwordx4 v250, s[60:61]
	s_mov_b32 m0, s4
	v_exp_f32_e32 v196, v104
	v_exp_f32_e32 v197, v105
	v_exp_f32_e32 v198, v106
	v_mfma_f32_32x32x16_bf16 v[114:129], v[4:7], v[8:11], v[114:129]
	ds_read_b128 v[12:15], v17 offset:6656
	ds_read_b128 v[102:105], v248 offset:3072
	v_exp_f32_e32 v17, v107
	v_exp_f32_e32 v199, v108
	v_exp_f32_e32 v200, v109
	s_waitcnt lgkmcnt(3)
	v_mfma_f32_32x32x16_bf16 v[130:145], v[178:181], v[186:189], v[130:145]
	v_exp_f32_e32 v201, v110
	ds_read_b64_tr_b16 v[4:5], v246 offset:24576
	ds_read_b64_tr_b16 v[6:7], v246 offset:25088
	v_exp_f32_e32 v202, v111
	v_exp_f32_e32 v178, v112
	v_cvt_pk_bf16_f32 v8, v190, v191
	v_cvt_pk_bf16_f32 v9, v192, v193
	v_cvt_pk_bf16_f32 v10, v194, v195
	v_cvt_pk_bf16_f32 v11, v196, v197
	v_mfma_f32_32x32x16_bf16 v[114:129], v[182:185], v[186:189], v[114:129]
	ds_read_b64_tr_b16 v[106:107], v246 offset:28672
	ds_read_b64_tr_b16 v[108:109], v246 offset:29184
	v_exp_f32_e32 v180, v82
	v_exp_f32_e32 v179, v113
	v_exp_f32_e32 v181, v83
	s_waitcnt lgkmcnt(4)
	v_mfma_f32_32x32x16_bf16 v[130:145], v[98:101], v[102:105], v[130:145]
	ds_read_b64_tr_b16 v[110:111], v246 offset:32768
	ds_read_b64_tr_b16 v[112:113], v246 offset:33280
	v_exp_f32_e32 v182, v84
	v_exp_f32_e32 v183, v85
	v_exp_f32_e32 v184, v86
	v_cvt_pk_bf16_f32 v82, v198, v17
	v_cvt_pk_bf16_f32 v83, v199, v200
	v_cvt_pk_bf16_f32 v84, v201, v202
	v_cvt_pk_bf16_f32 v85, v178, v179
	v_mfma_f32_32x32x16_bf16 v[114:129], v[12:15], v[102:105], v[114:129]
	ds_read_b64_tr_b16 v[98:99], v246 offset:36864
	ds_read_b64_tr_b16 v[100:101], v246 offset:37376
	v_exp_f32_e32 v185, v87
	v_exp_f32_e32 v186, v88
	v_exp_f32_e32 v187, v89
	s_waitcnt lgkmcnt(6)
	v_mfma_f32_32x32x16_bf16 v[18:33], v[8:11], v[4:7], v[18:33]
	v_add_f32_e32 v86, v190, v191
	ds_read_b64_tr_b16 v[12:13], v246 offset:25600
	ds_read_b64_tr_b16 v[14:15], v246 offset:26112
	v_add_f32_e32 v86, v192, v86
	v_exp_f32_e32 v103, v91
	v_add_f32_e32 v4, v193, v86
	v_add_f32_e32 v4, v194, v4
	v_add_f32_e32 v86, v195, v4
	v_exp_f32_e32 v102, v90
	s_waitcnt lgkmcnt(6)
	v_mfma_f32_32x32x16_bf16 v[34:49], v[8:11], v[106:109], v[34:49]
	ds_read_b64_tr_b16 v[4:5], v246 offset:29696
	ds_read_b64_tr_b16 v[6:7], v246 offset:30208
	v_add_f32_e32 v86, v196, v86
	v_add_f32_e32 v86, v197, v86
	v_add_f32_e32 v86, v198, v86
	v_exp_f32_e32 v104, v92
	v_add_f32_e32 v17, v17, v86
	v_exp_f32_e32 v105, v93
	s_waitcnt lgkmcnt(6)
	v_mfma_f32_32x32x16_bf16 v[50:65], v[8:11], v[110:113], v[50:65]
	ds_read_b64_tr_b16 v[86:87], v246 offset:33792
	ds_read_b64_tr_b16 v[88:89], v246 offset:34304
	v_add_f32_e32 v17, v199, v17
	v_add_f32_e32 v17, v200, v17
	v_add_f32_e32 v17, v201, v17
	v_exp_f32_e32 v106, v94
	v_add_f32_e32 v17, v202, v17
	v_exp_f32_e32 v107, v95
	s_waitcnt lgkmcnt(6)
	v_mfma_f32_32x32x16_bf16 v[66:81], v[8:11], v[98:101], v[66:81]
	ds_read_b64_tr_b16 v[90:91], v246 offset:37888
	ds_read_b64_tr_b16 v[92:93], v246 offset:38400
	v_add_f32_e32 v17, v178, v17
	v_add_f32_e32 v8, v179, v17
	v_add_f32_e32 v8, v180, v8
	v_exp_f32_e32 v108, v96
	v_add_f32_e32 v17, v181, v8
	v_exp_f32_e32 v109, v97
	s_waitcnt lgkmcnt(6)
; __device__ __forceinline__ float max3f(float a,float b,float c){float r;asm("v_max3_f32 %0, %1, %2, %3":"=v"(r):"v"(a),"v"(b),"v"(c));return r;}
; #define EXP1(x) x=__builtin_amdgcn_exp2f((x)-mh_)
; template<int THRL,bool FIRST> __device__ __forceinline__ void step_main(f32x16&p0,f32x16&p1,f32x16&n0,f32x16&n1,St&S,lds_cptr kpn,lds_cptr qp,lds_cptr vp,float*wsf,int r32,int hi,float&rm){
;     ...
;   PVG(0,pw0,vfa,4, p0[2],p0[3],p0[4],p0[5],   do{EXP1(p1[8]);EXP1(p1[9]);}while(0));
;   PVG(1,pw0,vfb,5, p0[6],p0[7],p0[8],p0[9], do{EXP1(p1[10]);EXP1(p1[11]);}while(0));
;   PVG(2,pw0,vfc,6, p0[10],p0[11],p0[12],p0[13], do{EXP1(p1[12]);EXP1(p1[13]);}while(0));
;   PVG(3,pw0,vfd,7, p0[14],p0[15],p1[0],p1[1],   do{EXP1(p1[14]);EXP1(p1[15]);}while(0));
;   PVG(4,pw1,vfa,8, p1[2],p1[3],p1[4],p1[5],   pw2=packw(p1,0));
;   PVG(5,pw1,vfb,9, p1[6],p1[7],p1[8],p1[9], pw3=packw(p1,8));
;   PVG(6,pw1,vfc,10, p1[10],p1[11],p1[12],p1[13], do{}while(0));
;   PVG(7,pw1,vfd,11, p1[14],p1[15],0.f,0.f, do{}while(0));
;   float ma,mb;
;     ...
;   PVG(8,pw2,vfa,12,0.f,0.f,0.f,0.f, do{ma=max3f(n0[0],n0[1],n1[0]);mb=max3f(n0[2],n0[3],n1[1]);PINAB();}while(0));
;   PVG(9,pw2,vfb,13,0.f,0.f,0.f,0.f, do{ma=max3f(ma,n1[2],n1[3]);mb=max3f(mb,n0[4],n0[5]);PINAB();}while(0));
;   PVG(10,pw2,vfc,14,0.f,0.f,0.f,0.f, do{ma=max3f(ma,n0[6],n0[7]);mb=max3f(mb,n1[4],n1[5]);PINAB();}while(0));
;   PVG(11,pw2,vfd,15,0.f,0.f,0.f,0.f, do{ma=max3f(ma,n1[6],n1[7]);mb=max3f(mb,n0[8],n0[9]);PINAB();}while(0));
;   PVG(12,pw3,vfa,16,0.f,0.f,0.f,0.f, do{ma=max3f(ma,n0[10],n0[11]);mb=max3f(mb,n1[8],n1[9]);PINAB();}while(0));
;   PVG(13,pw3,vfb,16,0.f,0.f,0.f,0.f, do{ma=max3f(ma,n1[10],n1[11]);mb=max3f(mb,n0[12],n0[13]);PINAB();}while(0));
;   PVG(14,pw3,vfc,16,0.f,0.f,0.f,0.f, do{ma=max3f(ma,n0[14],n0[15]);mb=max3f(mb,n1[12],n1[13]);PINAB();}while(0));
;   PVG(15,pw3,vfd,16,0.f,0.f,0.f,0.f, do{ma=max3f(ma,n1[14],n1[15]);ma=max2f(ma,mb);PINAB();}while(0));
;     ...
;   { auto rr=__builtin_amdgcn_permlane32_swap(__float_as_uint(ma),__float_as_uint(ma),false,false); rm=max2f(__uint_as_float(rr[0]),__uint_as_float(rr[1])); }
;     ...
;   S.l_reg+=sa;
; }
; template<int THRL> __device__ __forceinline__ void unit(int qb,const bf16*Q,const bf16*K,const bf16*V,bf16*O,char*shm){
;     ...
;       DMA_K(t+3,ks2); DMA_V(t+2,0);
;       step_main<THRL,false>(pB0,pB1,pA0,pA1,S,kp0+ks1,qp,vp0+VBUF,wsf,r32,hi,rm); A128_WAITBAR(); ROT();
	v_mfma_f32_32x32x16_bf16 v[18:33], v[82:85], v[12:15], v[18:33]
	ds_read_b64_tr_b16 v[8:9], v246 offset:26624
	ds_read_b64_tr_b16 v[10:11], v246 offset:27136
	v_add_f32_e32 v17, v182, v17
	v_add_f32_e32 v17, v183, v17
	v_add_f32_e32 v17, v184, v17
	v_add_f32_e32 v17, v185, v17
	v_cvt_pk_bf16_f32 v12, v180, v181
	v_cvt_pk_bf16_f32 v13, v182, v183
	v_cvt_pk_bf16_f32 v14, v184, v185
	v_cvt_pk_bf16_f32 v15, v186, v187
	s_waitcnt lgkmcnt(6)
	v_mfma_f32_32x32x16_bf16 v[34:49], v[82:85], v[4:7], v[34:49]
	ds_read_b64_tr_b16 v[94:95], v246 offset:30720
	ds_read_b64_tr_b16 v[96:97], v246 offset:31232
	v_add_f32_e32 v17, v186, v17
	v_add_f32_e32 v17, v187, v17
	v_add_f32_e32 v17, v102, v17
	v_add_f32_e32 v17, v103, v17
	v_cvt_pk_bf16_f32 v4, v102, v103
	v_cvt_pk_bf16_f32 v5, v104, v105
	v_cvt_pk_bf16_f32 v6, v106, v107
	v_cvt_pk_bf16_f32 v7, v108, v109
	s_waitcnt lgkmcnt(6)
	v_mfma_f32_32x32x16_bf16 v[50:65], v[82:85], v[86:89], v[50:65]
	ds_read_b64_tr_b16 v[98:99], v246 offset:34816
	ds_read_b64_tr_b16 v[100:101], v246 offset:35328
	v_add_f32_e32 v17, v104, v17
	v_add_f32_e32 v17, v105, v17
	v_add_f32_e32 v17, v106, v17
	v_add_f32_e32 v17, v107, v17
	s_waitcnt lgkmcnt(6)
	v_mfma_f32_32x32x16_bf16 v[66:81], v[82:85], v[90:93], v[66:81]
	ds_read_b64_tr_b16 v[86:87], v246 offset:38912
	ds_read_b64_tr_b16 v[88:89], v246 offset:39424
	v_add_f32_e32 v17, v108, v17
	v_add_f32_e32 v17, v109, v17
	v_add_f32_e32 v17, 0, v17
	s_waitcnt lgkmcnt(6)
	v_mfma_f32_32x32x16_bf16 v[18:33], v[12:15], v[8:11], v[18:33]
	ds_read_b64_tr_b16 v[82:83], v246 offset:27648
	ds_read_b64_tr_b16 v[84:85], v246 offset:28160
	v_max3_f32 v90, v130, v131, v114
	v_max3_f32 v91, v132, v133, v115
	s_nop 0
	s_waitcnt lgkmcnt(6)
	v_mfma_f32_32x32x16_bf16 v[34:49], v[12:15], v[94:97], v[34:49]
	ds_read_b64_tr_b16 v[8:9], v246 offset:31744
	ds_read_b64_tr_b16 v[10:11], v246 offset:32256
	v_max3_f32 v102, v90, v116, v117
	v_max3_f32 v103, v91, v134, v135
	s_nop 0
	s_waitcnt lgkmcnt(6)
	v_mfma_f32_32x32x16_bf16 v[50:65], v[12:15], v[98:101], v[50:65]
	ds_read_b64_tr_b16 v[90:91], v246 offset:35840
	ds_read_b64_tr_b16 v[92:93], v246 offset:36352
	v_max3_f32 v102, v102, v136, v137
	v_max3_f32 v103, v103, v118, v119
	s_nop 0
	s_waitcnt lgkmcnt(6)
	v_mfma_f32_32x32x16_bf16 v[66:81], v[12:15], v[86:89], v[66:81]
	ds_read_b64_tr_b16 v[94:95], v246 offset:39936
	ds_read_b64_tr_b16 v[96:97], v246 offset:40448
	v_max3_f32 v98, v102, v120, v121
	v_max3_f32 v99, v103, v138, v139
	s_nop 0
	s_waitcnt lgkmcnt(6)
	v_mfma_f32_32x32x16_bf16 v[18:33], v[4:7], v[82:85], v[18:33]
	v_max3_f32 v12, v98, v140, v141
	v_max3_f32 v13, v99, v122, v123
	s_nop 0
	s_waitcnt lgkmcnt(4)
	v_mfma_f32_32x32x16_bf16 v[34:49], v[4:7], v[8:11], v[34:49]
	v_max3_f32 v12, v12, v124, v125
	v_max3_f32 v13, v13, v142, v143
	s_nop 0
	s_waitcnt lgkmcnt(2)
	v_mfma_f32_32x32x16_bf16 v[50:65], v[4:7], v[90:93], v[50:65]
	v_max3_f32 v8, v12, v144, v145
	v_max3_f32 v9, v13, v126, v127
	s_nop 0
	s_waitcnt lgkmcnt(0)
	v_mfma_f32_32x32x16_bf16 v[66:81], v[4:7], v[94:97], v[66:81]
	v_max3_f32 v8, v8, v128, v129
	s_nop 0
	v_max_f32_e32 v8, v8, v9
	s_nop 0
	s_add_i32 s4, s88, 0x2000
	s_cmpk_lg_i32 s88, 0x4000
	s_cselect_b32 s91, s4, 0
	v_mov_b32_e32 v162, v8
	v_mov_b32_e32 v163, v8
	s_waitcnt vmcnt(0) lgkmcnt(0)
	s_barrier
	v_add_u32_e32 v178, s88, v249
	ds_read_b128 v[90:93], v178
	ds_read_b128 v[82:85], v178 offset:512
	ds_read_b128 v[12:15], v178 offset:2048
	ds_read_b128 v[4:7], v178 offset:2560
	ds_read_b128 v[86:89], v248
	ds_read_b128 v[8:11], v248 offset:1024
	v_permlane32_swap_b32_e32 v162, v163
	v_max_f32_e32 v94, v162, v163
	v_add_f32_e32 v17, v251, v17
	v_cmp_lt_f32_e32 vcc, s69, v94
	s_cbranch_vccz .LBB0_277
	v_max_f32_e32 v94, v94, v94
	v_max_f32_e32 v94, 0, v94
	v_exp_f32_e64 v95, -v94
	s_and_saveexec_b64 s[60:61], s[6:7]
	s_cbranch_execz .LBB0_276
	ds_write_b32 v16, v95
	s_branch .LBB0_276

; #define A128_WAITBAR() asm volatile("s_waitcnt vmcnt(0) lgkmcnt(0)\n\ts_barrier":::"memory")
; #define SB() __builtin_amdgcn_sched_barrier(0)
; #define MF32(a,b,c) __builtin_amdgcn_mfma_f32_32x32x16_bf16(a,b,c,0,0,0)
; #define EXP1(x) x=__builtin_amdgcn_exp2f((x)-mh_)
;   #define QF(d0) LDSQ(qp+(d0)*1024)
; template<int THRL,bool FIRST> __device__ __forceinline__ void step_main(f32x16&p0,f32x16&p1,f32x16&n0,f32x16&n1,St&S,lds_cptr kpn,lds_cptr qp,lds_cptr vp,float*wsf,int r32,int hi,float&rm){
;     ...
;   bf16x8 ka=KF(0),kb=KF(1),kc=KF(2),kd=KF(3),qa=QF(0),qb=QF(1);
;   decide<THRL,FIRST>(rm,S,wsf,r32,hi);
;   u32x4 pw0,pw1,pw2,pw3; const float mh_=S.mhat; const f32x16 z=f32x16{};
;   SB();
;   n0=MF32(ka,qa,z); ka=KF(4); EXP1(p0[0]);EXP1(p0[1]);EXP1(p0[2]); SB();
;   n1=MF32(kb,qa,z); kb=KF(5); qa=QF(2); EXP1(p0[3]);EXP1(p0[4]);EXP1(p0[5]); SB();
;   n0=MF32(kc,qb,n0);   kc=KF(6); EXP1(p0[6]);EXP1(p0[7]);EXP1(p0[8]); SB();
;   n1=MF32(kd,qb,n1);   kd=KF(7); qb=QF(3); EXP1(p0[9]);EXP1(p0[10]);EXP1(p0[11]); SB();
;   bf16x8 vfa=vfrag(vp,0);
;   n0=MF32(ka,qa,n0);   EXP1(p0[12]);EXP1(p0[13]);EXP1(p0[14]); pw0=packw(p0,0); SB();
;   bf16x8 vfb=vfrag(vp,1);
;   n1=MF32(kb,qa,n1);   EXP1(p0[15]);EXP1(p1[0]);EXP1(p1[1]); SB();
;   bf16x8 vfc=vfrag(vp,2);
;   n0=MF32(kc,qb,n0);   EXP1(p1[2]);EXP1(p1[3]);EXP1(p1[4]); pw1=packw(p0,8); SB();
;   bf16x8 vfd=vfrag(vp,3);
;   n1=MF32(kd,qb,n1);   EXP1(p1[5]);EXP1(p1[6]);EXP1(p1[7]); SB();
;     ...
;   float sa=p0[0]+p0[1];
;     ...
;   PVG(0,pw0,vfa,4, p0[2],p0[3],p0[4],p0[5],   do{EXP1(p1[8]);EXP1(p1[9]);}while(0));
;   PVG(1,pw0,vfb,5, p0[6],p0[7],p0[8],p0[9], do{EXP1(p1[10]);EXP1(p1[11]);}while(0));
;   PVG(2,pw0,vfc,6, p0[10],p0[11],p0[12],p0[13], do{EXP1(p1[12]);EXP1(p1[13]);}while(0));
;   PVG(3,pw0,vfd,7, p0[14],p0[15],p1[0],p1[1],   do{EXP1(p1[14]);EXP1(p1[15]);}while(0));
;   PVG(4,pw1,vfa,8, p1[2],p1[3],p1[4],p1[5],   pw2=packw(p1,0));
;   PVG(5,pw1,vfb,9, p1[6],p1[7],p1[8],p1[9], pw3=packw(p1,8));
;   PVG(6,pw1,vfc,10, p1[10],p1[11],p1[12],p1[13], do{}while(0));
;   PVG(7,pw1,vfd,11, p1[14],p1[15],0.f,0.f, do{}while(0));
; template<int THRL> __device__ __forceinline__ void unit(int qb,const bf16*Q,const bf16*K,const bf16*V,bf16*O,char*shm){
;     ...
;       DMA_K(t+2,ks2); DMA_V(t+1,VBUF);
;       step_main<THRL,false>(pA0,pA1,pB0,pB1,S,kp0+ks1,qp,vp0,wsf,r32,hi,rm); A128_WAITBAR(); ROT();
;       DMA_K(t+3,ks2); DMA_V(t+2,0);
.LBB0_435:
	s_add_i32 s88, s88, 2
	s_waitcnt lgkmcnt(1)
	v_mfma_f32_32x32x16_bf16 v[98:113], v[90:93], v[86:89], v[146:161]
	s_add_i32 s4, s89, s80
	s_mov_b32 s5, m0
	s_mov_b32 m0, s4
	s_nop 0
	global_load_lds_dwordx4 v252, s[50:51]
	s_mov_b32 m0, s5
	v_exp_f32_e32 v130, v130
	v_exp_f32_e32 v131, v131
	ds_read_b128 v[180:183], v178 offset:4096
	v_exp_f32_e32 v132, v132
	v_exp_f32_e32 v133, v133
	v_exp_f32_e32 v134, v134
	v_exp_f32_e32 v135, v135
	v_mfma_f32_32x32x16_bf16 v[82:97], v[82:85], v[86:89], v[146:161]
	ds_read_b128 v[184:187], v178 offset:4608
	ds_read_b128 v[188:191], v248 offset:2048
	s_add_u32 s58, s48, 0xc0000
	s_addc_u32 s59, s49, 0
	s_mov_b32 s4, m0
	s_mov_b32 m0, s78
	s_nop 0
	global_load_lds_dwordx4 v250, s[58:59]
	s_mov_b32 m0, s4
	s_waitcnt lgkmcnt(3)
	v_mfma_f32_32x32x16_bf16 v[98:113], v[12:15], v[8:11], v[98:113]
	ds_read_b128 v[192:195], v178 offset:6144
	s_add_u32 s58, s48, 0xc0080
	s_addc_u32 s59, s49, 0
	s_mov_b32 s4, m0
	s_mov_b32 m0, s79
	s_nop 0
	global_load_lds_dwordx4 v250, s[58:59]
	s_mov_b32 m0, s4
	v_exp_f32_e32 v136, v136
	v_exp_f32_e32 v137, v137
	v_exp_f32_e32 v138, v138
	v_mfma_f32_32x32x16_bf16 v[82:97], v[4:7], v[8:11], v[82:97]
	ds_read_b128 v[12:15], v178 offset:6656
	ds_read_b128 v[196:199], v248 offset:3072
	v_exp_f32_e32 v139, v139
	v_exp_f32_e32 v140, v140
	v_exp_f32_e32 v141, v141
	s_waitcnt lgkmcnt(3)
	v_mfma_f32_32x32x16_bf16 v[98:113], v[180:183], v[188:191], v[98:113]
	v_exp_f32_e32 v142, v142
	ds_read_b64_tr_b16 v[4:5], v246 offset:40960
	ds_read_b64_tr_b16 v[6:7], v246 offset:41472
	v_exp_f32_e32 v143, v143
	v_exp_f32_e32 v144, v144
	v_cvt_pk_bf16_f32 v8, v130, v131
	v_cvt_pk_bf16_f32 v9, v132, v133
	v_cvt_pk_bf16_f32 v10, v134, v135
	v_cvt_pk_bf16_f32 v11, v136, v137
	v_mfma_f32_32x32x16_bf16 v[82:97], v[184:187], v[188:191], v[82:97]
	ds_read_b64_tr_b16 v[178:179], v246 offset:45056
	ds_read_b64_tr_b16 v[180:181], v246 offset:45568
	v_exp_f32_e32 v145, v145
	v_exp_f32_e32 v114, v114
	v_exp_f32_e32 v115, v115
	s_waitcnt lgkmcnt(4)
	v_mfma_f32_32x32x16_bf16 v[98:113], v[192:195], v[196:199], v[98:113]
	ds_read_b64_tr_b16 v[182:183], v246 offset:49152
	ds_read_b64_tr_b16 v[184:185], v246 offset:49664
	v_exp_f32_e32 v116, v116
	v_exp_f32_e32 v117, v117
	v_exp_f32_e32 v118, v118
	v_cvt_pk_bf16_f32 v186, v138, v139
	v_cvt_pk_bf16_f32 v187, v140, v141
	v_cvt_pk_bf16_f32 v188, v142, v143
	v_cvt_pk_bf16_f32 v189, v144, v145
	v_mfma_f32_32x32x16_bf16 v[82:97], v[12:15], v[196:199], v[82:97]
	ds_read_b64_tr_b16 v[190:191], v246 offset:53248
	ds_read_b64_tr_b16 v[192:193], v246 offset:53760
	v_exp_f32_e32 v119, v119
	v_exp_f32_e32 v120, v120
	v_exp_f32_e32 v121, v121
	s_waitcnt lgkmcnt(6)
	v_mfma_f32_32x32x16_bf16 v[18:33], v[8:11], v[4:7], v[18:33]
	ds_read_b64_tr_b16 v[12:13], v246 offset:41984
	ds_read_b64_tr_b16 v[14:15], v246 offset:42496
	v_add_f32_e32 v194, v130, v131
	v_exp_f32_e32 v122, v122
	v_exp_f32_e32 v123, v123
	v_add_f32_e32 v194, v132, v194
	v_add_f32_e32 v4, v133, v194
	v_add_f32_e32 v4, v134, v4
	v_add_f32_e32 v194, v135, v4
	s_waitcnt lgkmcnt(6)
	v_mfma_f32_32x32x16_bf16 v[34:49], v[8:11], v[178:181], v[34:49]
	ds_read_b64_tr_b16 v[4:5], v246 offset:46080
	ds_read_b64_tr_b16 v[6:7], v246 offset:46592
	v_exp_f32_e32 v124, v124
	v_exp_f32_e32 v125, v125
	v_add_f32_e32 v194, v136, v194
	v_add_f32_e32 v178, v137, v194
	v_add_f32_e32 v178, v138, v178
	v_add_f32_e32 v194, v139, v178
	s_waitcnt lgkmcnt(6)
	v_mfma_f32_32x32x16_bf16 v[50:65], v[8:11], v[182:185], v[50:65]
	ds_read_b64_tr_b16 v[178:179], v246 offset:50176
	ds_read_b64_tr_b16 v[180:181], v246 offset:50688
	v_exp_f32_e32 v126, v126
	v_exp_f32_e32 v127, v127
	v_add_f32_e32 v194, v140, v194
	v_add_f32_e32 v182, v141, v194
	v_add_f32_e32 v182, v142, v182
	v_add_f32_e32 v194, v143, v182
	s_waitcnt lgkmcnt(6)
	v_mfma_f32_32x32x16_bf16 v[66:81], v[8:11], v[190:193], v[66:81]
	ds_read_b64_tr_b16 v[182:183], v246 offset:54272
	ds_read_b64_tr_b16 v[184:185], v246 offset:54784
	v_exp_f32_e32 v128, v128
	v_exp_f32_e32 v129, v129
	v_add_f32_e32 v194, v144, v194
	v_add_f32_e32 v8, v145, v194
	v_add_f32_e32 v8, v114, v8
	v_add_f32_e32 v190, v115, v8
	s_waitcnt lgkmcnt(6)
	v_mfma_f32_32x32x16_bf16 v[18:33], v[186:189], v[12:15], v[18:33]
	ds_read_b64_tr_b16 v[8:9], v246 offset:43008
	ds_read_b64_tr_b16 v[10:11], v246 offset:43520
	v_add_f32_e32 v190, v116, v190
	v_add_f32_e32 v190, v117, v190
	v_add_f32_e32 v190, v118, v190
	v_add_f32_e32 v194, v119, v190
	v_cvt_pk_bf16_f32 v12, v114, v115
	v_cvt_pk_bf16_f32 v13, v116, v117
	v_cvt_pk_bf16_f32 v14, v118, v119
	v_cvt_pk_bf16_f32 v15, v120, v121
	s_waitcnt lgkmcnt(6)
	v_mfma_f32_32x32x16_bf16 v[34:49], v[186:189], v[4:7], v[34:49]
	ds_read_b64_tr_b16 v[190:191], v246 offset:47104
	ds_read_b64_tr_b16 v[192:193], v246 offset:47616
	v_add_f32_e32 v194, v120, v194
	v_add_f32_e32 v194, v121, v194
	v_add_f32_e32 v194, v122, v194
	v_add_f32_e32 v198, v123, v194
	v_cvt_pk_bf16_f32 v4, v122, v123
	v_cvt_pk_bf16_f32 v5, v124, v125
	v_cvt_pk_bf16_f32 v6, v126, v127
	v_cvt_pk_bf16_f32 v7, v128, v129
	s_waitcnt lgkmcnt(6)
	v_mfma_f32_32x32x16_bf16 v[50:65], v[186:189], v[178:181], v[50:65]
	ds_read_b64_tr_b16 v[194:195], v246 offset:51200
	ds_read_b64_tr_b16 v[196:197], v246 offset:51712
	v_add_f32_e32 v198, v124, v198
	v_add_f32_e32 v198, v125, v198
	v_add_f32_e32 v198, v126, v198
	v_add_f32_e32 v198, v127, v198
	s_waitcnt lgkmcnt(6)
	v_mfma_f32_32x32x16_bf16 v[66:81], v[186:189], v[182:185], v[66:81]
	ds_read_b64_tr_b16 v[178:179], v246 offset:55296
	ds_read_b64_tr_b16 v[180:181], v246 offset:55808
	v_add_f32_e32 v198, v128, v198
	v_add_f32_e32 v198, v129, v198
	v_add_f32_e32 v198, 0, v198
	s_waitcnt lgkmcnt(6)
; __device__ __forceinline__ int crow(int r,int hi){return (r&3)+8*(r>>2)+4*hi;}
; __device__ __forceinline__ float max3f(float a,float b,float c){float r;asm("v_max3_f32 %0, %1, %2, %3":"=v"(r):"v"(a),"v"(b),"v"(c));return r;}
; __device__ __forceinline__ float max2f(float a,float b){float r;asm("v_max_f32_e32 %0, %1, %2":"=v"(r):"v"(a),"v"(b));return r;}
;   #define PVG(i,PW,VF,NEXTI,X0,X1,Y0,Y1,EXTRA) do{ S.o[(i)&3]=MF32(__builtin_bit_cast(bf16x8,PW),VF,S.o[(i)&3]); if((NEXTI)<16){ VF=vfrag(vp,(NEXTI)<16?(NEXTI):0); } sa+=X0; sa+=X1; sa+=Y0; sa+=Y1; EXTRA; SB(); }while(0)
; template<int THRL,bool FIRST> __device__ __forceinline__ void decide(float rm,St&S,float*wsf,int r32,int hi){
;   if(FIRST){ S.mhat=rm; }
;   else if(__any(rm-S.mhat>(float)THRL)){
;     const float dl=__builtin_fmaxf(rm-S.mhat,0.f); S.mhat+=dl;
;     const float f=__builtin_amdgcn_exp2f(-dl); S.l_reg*=f; if(hi==0)wsf[r32]=f;
;     asm volatile("s_waitcnt lgkmcnt(0)":::"memory");
;     #pragma unroll
;     for(int r=0;r<16;++r){ const float fr=wsf[crow(r,hi)];
;       #pragma unroll
;       for(int d=0;d<4;++d)S.o[d][r]*=fr; }
; template<int THRL,bool FIRST> __device__ __forceinline__ void step_main(f32x16&p0,f32x16&p1,f32x16&n0,f32x16&n1,St&S,lds_cptr kpn,lds_cptr qp,lds_cptr vp,float*wsf,int r32,int hi,float&rm){
;     ...
;   PVG(8,pw2,vfa,12,0.f,0.f,0.f,0.f, do{ma=max3f(n0[0],n0[1],n1[0]);mb=max3f(n0[2],n0[3],n1[1]);PINAB();}while(0));
;   PVG(9,pw2,vfb,13,0.f,0.f,0.f,0.f, do{ma=max3f(ma,n1[2],n1[3]);mb=max3f(mb,n0[4],n0[5]);PINAB();}while(0));
;   PVG(10,pw2,vfc,14,0.f,0.f,0.f,0.f, do{ma=max3f(ma,n0[6],n0[7]);mb=max3f(mb,n1[4],n1[5]);PINAB();}while(0));
;   PVG(11,pw2,vfd,15,0.f,0.f,0.f,0.f, do{ma=max3f(ma,n1[6],n1[7]);mb=max3f(mb,n0[8],n0[9]);PINAB();}while(0));
;   PVG(12,pw3,vfa,16,0.f,0.f,0.f,0.f, do{ma=max3f(ma,n0[10],n0[11]);mb=max3f(mb,n1[8],n1[9]);PINAB();}while(0));
;   PVG(13,pw3,vfb,16,0.f,0.f,0.f,0.f, do{ma=max3f(ma,n1[10],n1[11]);mb=max3f(mb,n0[12],n0[13]);PINAB();}while(0));
;   PVG(14,pw3,vfc,16,0.f,0.f,0.f,0.f, do{ma=max3f(ma,n0[14],n0[15]);mb=max3f(mb,n1[12],n1[13]);PINAB();}while(0));
;   PVG(15,pw3,vfd,16,0.f,0.f,0.f,0.f, do{ma=max3f(ma,n1[14],n1[15]);ma=max2f(ma,mb);PINAB();}while(0));
;     ...
;   { auto rr=__builtin_amdgcn_permlane32_swap(__float_as_uint(ma),__float_as_uint(ma),false,false); rm=max2f(__uint_as_float(rr[0]),__uint_as_float(rr[1])); }
;     ...
;   S.l_reg+=sa;
; }
	v_mfma_f32_32x32x16_bf16 v[18:33], v[12:15], v[8:11], v[18:33]
	ds_read_b64_tr_b16 v[182:183], v246 offset:44032
	ds_read_b64_tr_b16 v[184:185], v246 offset:44544
	v_max3_f32 v186, v98, v99, v82
	v_max3_f32 v187, v100, v101, v83
	s_nop 0
	s_waitcnt lgkmcnt(6)
	v_mfma_f32_32x32x16_bf16 v[34:49], v[12:15], v[190:193], v[34:49]
	ds_read_b64_tr_b16 v[8:9], v246 offset:48128
	ds_read_b64_tr_b16 v[10:11], v246 offset:48640
	v_max3_f32 v199, v186, v84, v85
	v_max3_f32 v200, v187, v102, v103
	s_nop 0
	s_waitcnt lgkmcnt(6)
	v_mfma_f32_32x32x16_bf16 v[50:65], v[12:15], v[194:197], v[50:65]
	ds_read_b64_tr_b16 v[186:187], v246 offset:52224
	ds_read_b64_tr_b16 v[188:189], v246 offset:52736
	v_max3_f32 v199, v199, v104, v105
	v_max3_f32 v200, v200, v86, v87
	s_nop 0
	s_waitcnt lgkmcnt(6)
	v_mfma_f32_32x32x16_bf16 v[66:81], v[12:15], v[178:181], v[66:81]
	ds_read_b64_tr_b16 v[190:191], v246 offset:56320
	ds_read_b64_tr_b16 v[192:193], v246 offset:56832
	v_max3_f32 v194, v199, v88, v89
	v_max3_f32 v195, v200, v106, v107
	s_nop 0
	s_waitcnt lgkmcnt(6)
	v_mfma_f32_32x32x16_bf16 v[18:33], v[4:7], v[182:185], v[18:33]
	v_max3_f32 v12, v194, v108, v109
	v_max3_f32 v13, v195, v90, v91
	s_nop 0
	s_waitcnt lgkmcnt(4)
	v_mfma_f32_32x32x16_bf16 v[34:49], v[4:7], v[8:11], v[34:49]
	v_max3_f32 v12, v12, v92, v93
	v_max3_f32 v13, v13, v110, v111
	s_nop 0
	s_waitcnt lgkmcnt(2)
	v_mfma_f32_32x32x16_bf16 v[50:65], v[4:7], v[186:189], v[50:65]
	v_max3_f32 v8, v12, v112, v113
	v_max3_f32 v9, v13, v94, v95
	s_nop 0
	s_waitcnt lgkmcnt(0)
	v_mfma_f32_32x32x16_bf16 v[66:81], v[4:7], v[190:193], v[66:81]
	v_max3_f32 v8, v8, v96, v97
	s_nop 0
	v_max_f32_e32 v8, v8, v9
	s_nop 0
	s_add_i32 s4, s89, 0x2000
	s_cmpk_lg_i32 s89, 0x4000
	s_cselect_b32 s86, s4, 0
	s_add_u32 s50, s50, 0x180000
	s_addc_u32 s51, s51, 0
	s_add_u32 s48, s48, 0x180000
	s_waitcnt vmcnt(0) lgkmcnt(0)
	s_barrier
	s_addc_u32 s49, s49, 0
	v_mov_b32_e32 v4, v8
	v_add_f32_e32 v251, v17, v198
	s_cmp_lt_u32 s88, s87
	v_permlane32_swap_b32_e32 v8, v4
	v_max_f32_e32 v178, v8, v4
	s_cbranch_scc0 .LBB0_443
.LBB0_436:
	v_add_u32_e32 v17, s89, v249
	ds_read_b128 v[122:125], v17
	ds_read_b128 v[114:117], v17 offset:512
	ds_read_b128 v[12:15], v17 offset:2048
	ds_read_b128 v[4:7], v17 offset:2560
	ds_read_b128 v[118:121], v248
	ds_read_b128 v[8:11], v248 offset:1024
	v_mov_b32_e32 v126, v178
	v_cmp_lt_f32_e32 vcc, s67, v126
	s_cbranch_vccz .LBB0_440
	v_max_f32_e32 v126, v126, v126
	v_max_f32_e32 v126, 0, v126
	v_exp_f32_e64 v127, -v126
	s_and_saveexec_b64 s[58:59], s[6:7]
	ds_write_b32 v16, v127
	s_or_b64 exec, exec, s[58:59]
	s_waitcnt lgkmcnt(0)
	v_add_u32_e32 v140, s76, v2
	ds_read_b128 v[128:131], v140 offset:64
	ds_read_b128 v[132:135], v140 offset:96
	ds_read_b128 v[136:139], v140
	ds_read_b128 v[140:143], v140 offset:32
	v_add_f32_e32 v247, v247, v126
	v_sub_f32_e32 v146, v146, v126
	v_sub_f32_e32 v147, v147, v126
	v_sub_f32_e32 v148, v148, v126
	v_sub_f32_e32 v149, v149, v126
	v_sub_f32_e32 v150, v150, v126
	v_sub_f32_e32 v151, v151, v126
	v_sub_f32_e32 v152, v152, v126
	v_sub_f32_e32 v153, v153, v126
	v_sub_f32_e32 v154, v154, v126
	v_sub_f32_e32 v155, v155, v126
	v_sub_f32_e32 v156, v156, v126
	v_sub_f32_e32 v157, v157, v126
	v_sub_f32_e32 v158, v158, v126
	v_sub_f32_e32 v159, v159, v126
	v_sub_f32_e32 v160, v160, v126
	v_sub_f32_e32 v161, v161, v126
	v_sub_f32_e32 v82, v82, v126
	v_sub_f32_e32 v83, v83, v126
	v_sub_f32_e32 v84, v84, v126
	v_sub_f32_e32 v85, v85, v126
	v_sub_f32_e32 v86, v86, v126
	v_sub_f32_e32 v87, v87, v126
	v_sub_f32_e32 v88, v88, v126
	v_sub_f32_e32 v89, v89, v126
	v_sub_f32_e32 v90, v90, v126
	v_sub_f32_e32 v91, v91, v126
	v_sub_f32_e32 v92, v92, v126
	v_sub_f32_e32 v93, v93, v126
	v_sub_f32_e32 v94, v94, v126
	v_sub_f32_e32 v95, v95, v126
	v_sub_f32_e32 v96, v96, v126
	v_sub_f32_e32 v97, v97, v126
	v_sub_f32_e32 v98, v98, v126
	v_sub_f32_e32 v99, v99, v126
	v_sub_f32_e32 v100, v100, v126
	v_sub_f32_e32 v101, v101, v126
	v_sub_f32_e32 v102, v102, v126
	v_sub_f32_e32 v103, v103, v126
	v_sub_f32_e32 v104, v104, v126
	v_sub_f32_e32 v105, v105, v126
	v_sub_f32_e32 v106, v106, v126
	v_sub_f32_e32 v107, v107, v126
	v_sub_f32_e32 v108, v108, v126
	v_sub_f32_e32 v109, v109, v126
	v_sub_f32_e32 v110, v110, v126
	v_sub_f32_e32 v111, v111, v126
	v_sub_f32_e32 v112, v112, v126
	v_sub_f32_e32 v113, v113, v126
	v_mul_f32_e32 v251, v251, v127
	s_waitcnt lgkmcnt(2)
	v_pk_mul_f32 v[30:31], v[30:31], v[132:133]
	v_pk_mul_f32 v[26:27], v[26:27], v[128:129]
	s_waitcnt lgkmcnt(0)
	v_pk_mul_f32 v[22:23], v[22:23], v[140:141]
	v_pk_mul_f32 v[32:33], v[32:33], v[134:135]
	v_pk_mul_f32 v[28:29], v[28:29], v[130:131]
	v_pk_mul_f32 v[24:25], v[24:25], v[142:143]
	v_pk_mul_f32 v[20:21], v[20:21], v[138:139]
	v_pk_mul_f32 v[18:19], v[18:19], v[136:137]
	v_pk_mul_f32 v[46:47], v[46:47], v[132:133]
	v_pk_mul_f32 v[42:43], v[42:43], v[128:129]
	v_pk_mul_f32 v[38:39], v[38:39], v[140:141]
	v_pk_mul_f32 v[48:49], v[48:49], v[134:135]
	v_pk_mul_f32 v[44:45], v[44:45], v[130:131]
	v_pk_mul_f32 v[40:41], v[40:41], v[142:143]
	v_pk_mul_f32 v[36:37], v[36:37], v[138:139]
	v_pk_mul_f32 v[34:35], v[34:35], v[136:137]
	v_pk_mul_f32 v[62:63], v[62:63], v[132:133]
	v_pk_mul_f32 v[58:59], v[58:59], v[128:129]
	v_pk_mul_f32 v[54:55], v[54:55], v[140:141]
	v_pk_mul_f32 v[64:65], v[64:65], v[134:135]
	v_pk_mul_f32 v[60:61], v[60:61], v[130:131]
	v_pk_mul_f32 v[56:57], v[56:57], v[142:143]
	v_pk_mul_f32 v[52:53], v[52:53], v[138:139]
	v_pk_mul_f32 v[50:51], v[50:51], v[136:137]
	v_pk_mul_f32 v[78:79], v[78:79], v[132:133]
	v_pk_mul_f32 v[74:75], v[74:75], v[128:129]
	v_pk_mul_f32 v[70:71], v[70:71], v[140:141]
	v_pk_mul_f32 v[80:81], v[80:81], v[134:135]
	v_pk_mul_f32 v[76:77], v[76:77], v[130:131]
	v_pk_mul_f32 v[72:73], v[72:73], v[142:143]
	v_pk_mul_f32 v[68:69], v[68:69], v[138:139]
	v_pk_mul_f32 v[66:67], v[66:67], v[136:137]
; #define A128_WAITBAR() asm volatile("s_waitcnt vmcnt(0) lgkmcnt(0)\n\ts_barrier":::"memory")
; #define SB() __builtin_amdgcn_sched_barrier(0)
; #define MF32(a,b,c) __builtin_amdgcn_mfma_f32_32x32x16_bf16(a,b,c,0,0,0)
; #define EXP1(x) x=__builtin_amdgcn_exp2f((x)-mh_)
; __device__ __forceinline__ bf16x8 vfrag(lds_cptr vp,int i){ const s16x4 lo=vtr(vp+(i&3)*4096+(i>>2)*1024), hh=vtr(vp+(i&3)*4096+(i>>2)*1024+512); return (bf16x8){lo[0],lo[1],lo[2],lo[3],hh[0],hh[1],hh[2],hh[3]}; }
;   #define KF(i) LDSQ(kpn+((i)>>1)*2048+((i)&1)*512)
;   #define QF(d0) LDSQ(qp+(d0)*1024)
; template<int THRL,bool FIRST> __device__ __forceinline__ void step_main(f32x16&p0,f32x16&p1,f32x16&n0,f32x16&n1,St&S,lds_cptr kpn,lds_cptr qp,lds_cptr vp,float*wsf,int r32,int hi,float&rm){
;     ...
;   bf16x8 ka=KF(0),kb=KF(1),kc=KF(2),kd=KF(3),qa=QF(0),qb=QF(1);
;   decide<THRL,FIRST>(rm,S,wsf,r32,hi);
;   u32x4 pw0,pw1,pw2,pw3; const float mh_=S.mhat; const f32x16 z=f32x16{};
;   SB();
;   n0=MF32(ka,qa,z); ka=KF(4); EXP1(p0[0]);EXP1(p0[1]);EXP1(p0[2]); SB();
;   n1=MF32(kb,qa,z); kb=KF(5); qa=QF(2); EXP1(p0[3]);EXP1(p0[4]);EXP1(p0[5]); SB();
;   n0=MF32(kc,qb,n0);   kc=KF(6); EXP1(p0[6]);EXP1(p0[7]);EXP1(p0[8]); SB();
;   n1=MF32(kd,qb,n1);   kd=KF(7); qb=QF(3); EXP1(p0[9]);EXP1(p0[10]);EXP1(p0[11]); SB();
;   bf16x8 vfa=vfrag(vp,0);
;   n0=MF32(ka,qa,n0);   EXP1(p0[12]);EXP1(p0[13]);EXP1(p0[14]); pw0=packw(p0,0); SB();
;   bf16x8 vfb=vfrag(vp,1);
;   n1=MF32(kb,qa,n1);   EXP1(p0[15]);EXP1(p1[0]);EXP1(p1[1]); SB();
;   bf16x8 vfc=vfrag(vp,2);
;   n0=MF32(kc,qb,n0);   EXP1(p1[2]);EXP1(p1[3]);EXP1(p1[4]); pw1=packw(p0,8); SB();
;   bf16x8 vfd=vfrag(vp,3);
;   n1=MF32(kd,qb,n1);   EXP1(p1[5]);EXP1(p1[6]);EXP1(p1[7]); SB();
;     ...
;   float sa=p0[0]+p0[1];
;     ...
;   PVG(0,pw0,vfa,4, p0[2],p0[3],p0[4],p0[5],   do{EXP1(p1[8]);EXP1(p1[9]);}while(0));
;   PVG(1,pw0,vfb,5, p0[6],p0[7],p0[8],p0[9], do{EXP1(p1[10]);EXP1(p1[11]);}while(0));
;   PVG(2,pw0,vfc,6, p0[10],p0[11],p0[12],p0[13], do{EXP1(p1[12]);EXP1(p1[13]);}while(0));
;   PVG(3,pw0,vfd,7, p0[14],p0[15],p1[0],p1[1],   do{EXP1(p1[14]);EXP1(p1[15]);}while(0));
; template<int THRL> __device__ __forceinline__ void unit(int qb,const bf16*Q,const bf16*K,const bf16*V,bf16*O,char*shm){
;     ...
;       DMA_K(t+2,ks2); DMA_V(t+1,VBUF);
;       step_main<THRL,false>(pA0,pA1,pB0,pB1,S,kp0+ks1,qp,vp0,wsf,r32,hi,rm); A128_WAITBAR(); ROT();
.LBB0_440:
	s_waitcnt lgkmcnt(1)
	v_mfma_f32_32x32x16_bf16 v[130:145], v[122:125], v[118:121], v[146:161]
	ds_read_b128 v[178:181], v17 offset:4096
	s_add_i32 s4, s86, s80
	s_add_u32 s58, s50, 0xfff40000
	s_addc_u32 s59, s51, -1
	s_mov_b32 s5, m0
	s_mov_b32 m0, s4
	s_nop 0
	global_load_lds_dwordx4 v252, s[58:59]
	s_mov_b32 m0, s5
	v_exp_f32_e32 v190, v98
	v_exp_f32_e32 v191, v99
	v_exp_f32_e32 v192, v100
	v_mfma_f32_32x32x16_bf16 v[114:129], v[114:117], v[118:121], v[146:161]
	ds_read_b128 v[182:185], v17 offset:4608
	ds_read_b128 v[186:189], v248 offset:2048
	s_mov_b32 s4, m0
	s_mov_b32 m0, s77
	s_nop 0
	global_load_lds_dwordx4 v250, s[48:49]
	s_mov_b32 m0, s4
	v_exp_f32_e32 v193, v101
	v_exp_f32_e32 v194, v102
	v_exp_f32_e32 v195, v103
	s_waitcnt lgkmcnt(3)
	v_mfma_f32_32x32x16_bf16 v[130:145], v[12:15], v[8:11], v[130:145]
	ds_read_b128 v[98:101], v17 offset:6144
	s_add_u32 s58, s48, 0x80
	s_addc_u32 s59, s49, 0
	s_mov_b32 s4, m0
	s_mov_b32 m0, s39
	s_nop 0
	global_load_lds_dwordx4 v250, s[58:59]
	s_mov_b32 m0, s4
	v_exp_f32_e32 v196, v104
	v_exp_f32_e32 v197, v105
	v_exp_f32_e32 v198, v106
	v_mfma_f32_32x32x16_bf16 v[114:129], v[4:7], v[8:11], v[114:129]
	ds_read_b128 v[12:15], v17 offset:6656
	ds_read_b128 v[102:105], v248 offset:3072
	v_exp_f32_e32 v17, v107
	v_exp_f32_e32 v199, v108
	v_exp_f32_e32 v200, v109
	s_waitcnt lgkmcnt(3)
	v_mfma_f32_32x32x16_bf16 v[130:145], v[178:181], v[186:189], v[130:145]
	v_exp_f32_e32 v201, v110
	ds_read_b64_tr_b16 v[4:5], v246 offset:24576
	ds_read_b64_tr_b16 v[6:7], v246 offset:25088
	v_exp_f32_e32 v202, v111
	v_exp_f32_e32 v178, v112
	v_cvt_pk_bf16_f32 v8, v190, v191
	v_cvt_pk_bf16_f32 v9, v192, v193
	v_cvt_pk_bf16_f32 v10, v194, v195
	v_cvt_pk_bf16_f32 v11, v196, v197
	v_mfma_f32_32x32x16_bf16 v[114:129], v[182:185], v[186:189], v[114:129]
	ds_read_b64_tr_b16 v[106:107], v246 offset:28672
	ds_read_b64_tr_b16 v[108:109], v246 offset:29184
	v_exp_f32_e32 v180, v82
	v_exp_f32_e32 v179, v113
	v_exp_f32_e32 v181, v83
	s_waitcnt lgkmcnt(4)
	v_mfma_f32_32x32x16_bf16 v[130:145], v[98:101], v[102:105], v[130:145]
	ds_read_b64_tr_b16 v[110:111], v246 offset:32768
	ds_read_b64_tr_b16 v[112:113], v246 offset:33280
	v_exp_f32_e32 v182, v84
	v_exp_f32_e32 v183, v85
	v_exp_f32_e32 v184, v86
	v_cvt_pk_bf16_f32 v82, v198, v17
	v_cvt_pk_bf16_f32 v83, v199, v200
	v_cvt_pk_bf16_f32 v84, v201, v202
	v_cvt_pk_bf16_f32 v85, v178, v179
	v_mfma_f32_32x32x16_bf16 v[114:129], v[12:15], v[102:105], v[114:129]
	ds_read_b64_tr_b16 v[98:99], v246 offset:36864
	ds_read_b64_tr_b16 v[100:101], v246 offset:37376
	v_exp_f32_e32 v185, v87
	v_exp_f32_e32 v186, v88
	v_exp_f32_e32 v187, v89
	s_waitcnt lgkmcnt(6)
	v_mfma_f32_32x32x16_bf16 v[18:33], v[8:11], v[4:7], v[18:33]
	v_add_f32_e32 v86, v190, v191
	ds_read_b64_tr_b16 v[12:13], v246 offset:25600
	ds_read_b64_tr_b16 v[14:15], v246 offset:26112
	v_add_f32_e32 v86, v192, v86
	v_exp_f32_e32 v103, v91
	v_add_f32_e32 v4, v193, v86
	v_add_f32_e32 v4, v194, v4
	v_add_f32_e32 v86, v195, v4
	v_exp_f32_e32 v102, v90
	s_waitcnt lgkmcnt(6)
	v_mfma_f32_32x32x16_bf16 v[34:49], v[8:11], v[106:109], v[34:49]
	ds_read_b64_tr_b16 v[4:5], v246 offset:29696
	ds_read_b64_tr_b16 v[6:7], v246 offset:30208
	v_add_f32_e32 v86, v196, v86
	v_add_f32_e32 v86, v197, v86
	v_add_f32_e32 v86, v198, v86
	v_exp_f32_e32 v104, v92
	v_add_f32_e32 v17, v17, v86
	v_exp_f32_e32 v105, v93
	s_waitcnt lgkmcnt(6)
	v_mfma_f32_32x32x16_bf16 v[50:65], v[8:11], v[110:113], v[50:65]
	ds_read_b64_tr_b16 v[86:87], v246 offset:33792
	ds_read_b64_tr_b16 v[88:89], v246 offset:34304
	v_add_f32_e32 v17, v199, v17
	v_add_f32_e32 v17, v200, v17
	v_add_f32_e32 v17, v201, v17
	v_exp_f32_e32 v106, v94
	v_add_f32_e32 v17, v202, v17
	v_exp_f32_e32 v107, v95
	s_waitcnt lgkmcnt(6)
	v_mfma_f32_32x32x16_bf16 v[66:81], v[8:11], v[98:101], v[66:81]
	ds_read_b64_tr_b16 v[90:91], v246 offset:37888
	ds_read_b64_tr_b16 v[92:93], v246 offset:38400
	v_add_f32_e32 v17, v178, v17
	v_add_f32_e32 v8, v179, v17
	v_add_f32_e32 v8, v180, v8
	v_exp_f32_e32 v108, v96
	v_add_f32_e32 v17, v181, v8
	v_exp_f32_e32 v109, v97
	s_waitcnt lgkmcnt(6)
; __device__ __forceinline__ float max3f(float a,float b,float c){float r;asm("v_max3_f32 %0, %1, %2, %3":"=v"(r):"v"(a),"v"(b),"v"(c));return r;}
; #define EXP1(x) x=__builtin_amdgcn_exp2f((x)-mh_)
; template<int THRL,bool FIRST> __device__ __forceinline__ void step_main(f32x16&p0,f32x16&p1,f32x16&n0,f32x16&n1,St&S,lds_cptr kpn,lds_cptr qp,lds_cptr vp,float*wsf,int r32,int hi,float&rm){
;     ...
;   PVG(0,pw0,vfa,4, p0[2],p0[3],p0[4],p0[5],   do{EXP1(p1[8]);EXP1(p1[9]);}while(0));
;   PVG(1,pw0,vfb,5, p0[6],p0[7],p0[8],p0[9], do{EXP1(p1[10]);EXP1(p1[11]);}while(0));
;   PVG(2,pw0,vfc,6, p0[10],p0[11],p0[12],p0[13], do{EXP1(p1[12]);EXP1(p1[13]);}while(0));
;   PVG(3,pw0,vfd,7, p0[14],p0[15],p1[0],p1[1],   do{EXP1(p1[14]);EXP1(p1[15]);}while(0));
;   PVG(4,pw1,vfa,8, p1[2],p1[3],p1[4],p1[5],   pw2=packw(p1,0));
;   PVG(5,pw1,vfb,9, p1[6],p1[7],p1[8],p1[9], pw3=packw(p1,8));
;   PVG(6,pw1,vfc,10, p1[10],p1[11],p1[12],p1[13], do{}while(0));
;   PVG(7,pw1,vfd,11, p1[14],p1[15],0.f,0.f, do{}while(0));
;   float ma,mb;
;     ...
;   PVG(8,pw2,vfa,12,0.f,0.f,0.f,0.f, do{ma=max3f(n0[0],n0[1],n1[0]);mb=max3f(n0[2],n0[3],n1[1]);PINAB();}while(0));
;   PVG(9,pw2,vfb,13,0.f,0.f,0.f,0.f, do{ma=max3f(ma,n1[2],n1[3]);mb=max3f(mb,n0[4],n0[5]);PINAB();}while(0));
;   PVG(10,pw2,vfc,14,0.f,0.f,0.f,0.f, do{ma=max3f(ma,n0[6],n0[7]);mb=max3f(mb,n1[4],n1[5]);PINAB();}while(0));
;   PVG(11,pw2,vfd,15,0.f,0.f,0.f,0.f, do{ma=max3f(ma,n1[6],n1[7]);mb=max3f(mb,n0[8],n0[9]);PINAB();}while(0));
;   PVG(12,pw3,vfa,16,0.f,0.f,0.f,0.f, do{ma=max3f(ma,n0[10],n0[11]);mb=max3f(mb,n1[8],n1[9]);PINAB();}while(0));
;   PVG(13,pw3,vfb,16,0.f,0.f,0.f,0.f, do{ma=max3f(ma,n1[10],n1[11]);mb=max3f(mb,n0[12],n0[13]);PINAB();}while(0));
;   PVG(14,pw3,vfc,16,0.f,0.f,0.f,0.f, do{ma=max3f(ma,n0[14],n0[15]);mb=max3f(mb,n1[12],n1[13]);PINAB();}while(0));
;   PVG(15,pw3,vfd,16,0.f,0.f,0.f,0.f, do{ma=max3f(ma,n1[14],n1[15]);ma=max2f(ma,mb);PINAB();}while(0));
;     ...
;   { auto rr=__builtin_amdgcn_permlane32_swap(__float_as_uint(ma),__float_as_uint(ma),false,false); rm=max2f(__uint_as_float(rr[0]),__uint_as_float(rr[1])); }
;     ...
;   S.l_reg+=sa;
; }
; template<int THRL> __device__ __forceinline__ void unit(int qb,const bf16*Q,const bf16*K,const bf16*V,bf16*O,char*shm){
;     ...
;       DMA_K(t+3,ks2); DMA_V(t+2,0);
;       step_main<THRL,false>(pB0,pB1,pA0,pA1,S,kp0+ks1,qp,vp0+VBUF,wsf,r32,hi,rm); A128_WAITBAR(); ROT();
	v_mfma_f32_32x32x16_bf16 v[18:33], v[82:85], v[12:15], v[18:33]
	ds_read_b64_tr_b16 v[8:9], v246 offset:26624
	ds_read_b64_tr_b16 v[10:11], v246 offset:27136
	v_add_f32_e32 v17, v182, v17
	v_add_f32_e32 v17, v183, v17
	v_add_f32_e32 v17, v184, v17
	v_add_f32_e32 v17, v185, v17
	v_cvt_pk_bf16_f32 v12, v180, v181
	v_cvt_pk_bf16_f32 v13, v182, v183
	v_cvt_pk_bf16_f32 v14, v184, v185
	v_cvt_pk_bf16_f32 v15, v186, v187
	s_waitcnt lgkmcnt(6)
	v_mfma_f32_32x32x16_bf16 v[34:49], v[82:85], v[4:7], v[34:49]
	ds_read_b64_tr_b16 v[94:95], v246 offset:30720
	ds_read_b64_tr_b16 v[96:97], v246 offset:31232
	v_add_f32_e32 v17, v186, v17
	v_add_f32_e32 v17, v187, v17
	v_add_f32_e32 v17, v102, v17
	v_add_f32_e32 v17, v103, v17
	v_cvt_pk_bf16_f32 v4, v102, v103
	v_cvt_pk_bf16_f32 v5, v104, v105
	v_cvt_pk_bf16_f32 v6, v106, v107
	v_cvt_pk_bf16_f32 v7, v108, v109
	s_waitcnt lgkmcnt(6)
	v_mfma_f32_32x32x16_bf16 v[50:65], v[82:85], v[86:89], v[50:65]
	ds_read_b64_tr_b16 v[98:99], v246 offset:34816
	ds_read_b64_tr_b16 v[100:101], v246 offset:35328
	v_add_f32_e32 v17, v104, v17
	v_add_f32_e32 v17, v105, v17
	v_add_f32_e32 v17, v106, v17
	v_add_f32_e32 v17, v107, v17
	s_waitcnt lgkmcnt(6)
	v_mfma_f32_32x32x16_bf16 v[66:81], v[82:85], v[90:93], v[66:81]
	ds_read_b64_tr_b16 v[86:87], v246 offset:38912
	ds_read_b64_tr_b16 v[88:89], v246 offset:39424
	v_add_f32_e32 v17, v108, v17
	v_add_f32_e32 v17, v109, v17
	v_add_f32_e32 v17, 0, v17
	s_waitcnt lgkmcnt(6)
	v_mfma_f32_32x32x16_bf16 v[18:33], v[12:15], v[8:11], v[18:33]
	ds_read_b64_tr_b16 v[82:83], v246 offset:27648
	ds_read_b64_tr_b16 v[84:85], v246 offset:28160
	v_max3_f32 v90, v130, v131, v114
	v_max3_f32 v91, v132, v133, v115
	s_nop 0
	s_waitcnt lgkmcnt(6)
	v_mfma_f32_32x32x16_bf16 v[34:49], v[12:15], v[94:97], v[34:49]
	ds_read_b64_tr_b16 v[8:9], v246 offset:31744
	ds_read_b64_tr_b16 v[10:11], v246 offset:32256
	v_max3_f32 v102, v90, v116, v117
	v_max3_f32 v103, v91, v134, v135
	s_nop 0
	s_waitcnt lgkmcnt(6)
	v_mfma_f32_32x32x16_bf16 v[50:65], v[12:15], v[98:101], v[50:65]
	ds_read_b64_tr_b16 v[90:91], v246 offset:35840
	ds_read_b64_tr_b16 v[92:93], v246 offset:36352
	v_max3_f32 v102, v102, v136, v137
	v_max3_f32 v103, v103, v118, v119
	s_nop 0
	s_waitcnt lgkmcnt(6)
	v_mfma_f32_32x32x16_bf16 v[66:81], v[12:15], v[86:89], v[66:81]
	ds_read_b64_tr_b16 v[94:95], v246 offset:39936
	ds_read_b64_tr_b16 v[96:97], v246 offset:40448
	v_max3_f32 v98, v102, v120, v121
	v_max3_f32 v99, v103, v138, v139
	s_nop 0
	s_waitcnt lgkmcnt(6)
	v_mfma_f32_32x32x16_bf16 v[18:33], v[4:7], v[82:85], v[18:33]
	v_max3_f32 v12, v98, v140, v141
	v_max3_f32 v13, v99, v122, v123
	s_nop 0
	s_waitcnt lgkmcnt(4)
	v_mfma_f32_32x32x16_bf16 v[34:49], v[4:7], v[8:11], v[34:49]
	v_max3_f32 v12, v12, v124, v125
	v_max3_f32 v13, v13, v142, v143
	s_nop 0
	s_waitcnt lgkmcnt(2)
	v_mfma_f32_32x32x16_bf16 v[50:65], v[4:7], v[90:93], v[50:65]
	v_max3_f32 v8, v12, v144, v145
	v_max3_f32 v9, v13, v126, v127
	s_nop 0
	s_waitcnt lgkmcnt(0)
	v_mfma_f32_32x32x16_bf16 v[66:81], v[4:7], v[94:97], v[66:81]
	v_max3_f32 v8, v8, v128, v129
	s_nop 0
	v_max_f32_e32 v8, v8, v9
	s_nop 0
	s_add_i32 s4, s86, 0x2000
	s_cmpk_lg_i32 s86, 0x4000
	s_cselect_b32 s89, s4, 0
	v_mov_b32_e32 v162, v8
	v_mov_b32_e32 v163, v8
	s_waitcnt vmcnt(0) lgkmcnt(0)
	s_barrier
	v_add_u32_e32 v178, s86, v249
	ds_read_b128 v[90:93], v178
	ds_read_b128 v[82:85], v178 offset:512
	ds_read_b128 v[12:15], v178 offset:2048
	ds_read_b128 v[4:7], v178 offset:2560
	ds_read_b128 v[86:89], v248
	ds_read_b128 v[8:11], v248 offset:1024
	v_permlane32_swap_b32_e32 v162, v163
	v_max_f32_e32 v94, v162, v163
	v_add_f32_e32 v17, v251, v17
	v_cmp_lt_f32_e32 vcc, s67, v94
	s_cbranch_vccz .LBB0_435
	v_max_f32_e32 v94, v94, v94
	v_max_f32_e32 v94, 0, v94
	v_exp_f32_e64 v95, -v94
	s_and_saveexec_b64 s[58:59], s[6:7]
	s_cbranch_execz .LBB0_434
	ds_write_b32 v16, v95
	s_branch .LBB0_434
